# direct HBM to LDS loads (lever 5): P1 bias-GEMV modulation vector staged with 16 global_load_lds_dword per wave instead of VGPR loads plus ds_write
# speedup vs baseline: 1.0039x; 1.0011x over previous
; #define LAS __attribute__((address_space(3)))
; __device__ __forceinline__ void gemv_load(const float* W, int N, int n0, f32x4 (&wv)[16], int tid) {
;     const int cgp = tid & 7, kg = tid >> 3;
; #pragma unroll
;     for (int i = 0; i < 16; ++i) wv[i] = __builtin_nontemporal_load((const f32x4*)(W + (size_t)(kg + 64 * i) * N + n0 + 4 * cgp));
; }
; __device__ __forceinline__ void phase1(const Params& p, LAS unsigned char* lds, int tid, int lane, int wave) {
;     const float* mod = (const float*)(p.ws + WS_MOD);
;     if (blockIdx.x < 176) {
;         LAS float* vecs = (LAS float*)lds; LAS float* red = (LAS float*)(lds + 32768);
;         f32x4 wv[16]; gemv_load(p.w_up, 2 * DFF, 32 * blockIdx.x, wv, tid);
;         for (int i = tid; i < 8192; i += 512) vecs[i] = mod[(i >> 10) * NMOD + 3072 + (i & 1023)];
;         __syncthreads();
.Lgb1_done:
.LBB0_95:
	s_or_b64 exec, exec, s[6:7]
	s_waitcnt lgkmcnt(0)
	s_barrier
	s_load_dwordx2 s[34:35], s[96:97], 0
	s_load_dwordx2 s[4:5], s[96:97], 8
	s_load_dwordx2 s[6:7], s[96:97], 16
	s_load_dwordx2 s[8:9], s[96:97], 24
	s_load_dwordx2 s[38:39], s[96:97], 32
	s_load_dwordx2 s[40:41], s[96:97], 40
	s_load_dwordx2 s[36:37], s[96:97], 48
	s_load_dwordx2 s[10:11], s[96:97], 56
	s_load_dwordx2 s[12:13], s[96:97], 64
	s_load_dwordx2 s[14:15], s[96:97], 72
	s_load_dwordx2 s[42:43], s[96:97], 80
	s_load_dwordx2 s[16:17], s[96:97], 88
	s_load_dwordx2 s[44:45], s[96:97], 96
	s_load_dwordx2 s[18:19], s[96:97], 104
	s_load_dwordx2 s[46:47], s[96:97], 112
	s_load_dwordx2 s[20:21], s[96:97], 120
	s_load_dwordx2 s[30:31], s[96:97], 128
	s_waitcnt lgkmcnt(0)
	s_cmpk_gt_u32 s2, 0xaf
	s_cselect_b64 s[48:49], -1, 0
	s_and_b64 vcc, exec, s[48:49]
	v_lshrrev_b32_e32 v97, 9, v208
	s_cbranch_vccnz .LBB0_112
	s_add_u32 s50, s30, 0x3000
	s_addc_u32 s51, s31, 0
	s_lshl_b32 s52, s58, 8
	s_add_i32 m0, s52, 0x0
	s_nop 0
	global_load_lds_dword v96, s[50:51]
	global_load_lds_dword v96, s[50:51] offset:2048
	s_add_u32 s50, s50, 0x6000
	s_addc_u32 s51, s51, 0
	s_add_i32 m0, s52, 0x1000
	s_nop 0
	global_load_lds_dword v96, s[50:51]
	global_load_lds_dword v96, s[50:51] offset:2048
	s_add_u32 s50, s50, 0x6000
	s_addc_u32 s51, s51, 0
	s_add_i32 m0, s52, 0x2000
	s_nop 0
	global_load_lds_dword v96, s[50:51]
	global_load_lds_dword v96, s[50:51] offset:2048
	s_add_u32 s50, s50, 0x6000
	s_addc_u32 s51, s51, 0
	s_add_i32 m0, s52, 0x3000
	s_nop 0
	global_load_lds_dword v96, s[50:51]
	global_load_lds_dword v96, s[50:51] offset:2048
	s_add_u32 s50, s50, 0x6000
	s_addc_u32 s51, s51, 0
	s_add_i32 m0, s52, 0x4000
	s_nop 0
	global_load_lds_dword v96, s[50:51]
	global_load_lds_dword v96, s[50:51] offset:2048
	s_add_u32 s50, s50, 0x6000
	s_addc_u32 s51, s51, 0
	s_add_i32 m0, s52, 0x5000
	s_nop 0
	global_load_lds_dword v96, s[50:51]
	global_load_lds_dword v96, s[50:51] offset:2048
	s_add_u32 s50, s50, 0x6000
	s_addc_u32 s51, s51, 0
	s_add_i32 m0, s52, 0x6000
	s_nop 0
	global_load_lds_dword v96, s[50:51]
	global_load_lds_dword v96, s[50:51] offset:2048
	s_add_u32 s50, s50, 0x6000
	s_addc_u32 s51, s51, 0
	s_add_i32 m0, s52, 0x7000
	s_nop 0
	global_load_lds_dword v96, s[50:51]
	global_load_lds_dword v96, s[50:51] offset:2048
	s_lshl_b32 s8, s2, 5
	s_mov_b32 s9, 0
	s_lshl_b64 s[4:5], s[8:9], 2
	s_add_u32 s4, s44, s4
	v_and_b32_e32 v66, 28, v96
	s_addc_u32 s5, s45, s5
	v_mov_b32_e32 v69, 0
	v_lshlrev_b32_e32 v68, 2, v66
	v_mul_u32_u24_e32 v64, 0x1600, v174
	v_lshl_add_u64 v[0:1], s[4:5], 0, v[68:69]
	v_lshlrev_b32_e32 v68, 2, v64
	v_lshl_add_u64 v[56:57], v[0:1], 0, v[68:69]
	s_mov_b32 s0, 0x160000
	v_add_co_u32_e32 v8, vcc, s0, v56
	s_mov_b32 s0, 0x2c0000
	s_nop 0
	v_addc_co_u32_e32 v9, vcc, 0, v57, vcc
	v_add_co_u32_e32 v16, vcc, s0, v56
	s_mov_b32 s0, 0x420000
	s_nop 0
	v_addc_co_u32_e32 v17, vcc, 0, v57, vcc
	v_add_co_u32_e32 v18, vcc, s0, v56
	s_mov_b32 s0, 0x580000
	s_nop 0
	v_addc_co_u32_e32 v19, vcc, 0, v57, vcc
	v_add_co_u32_e32 v24, vcc, s0, v56
	s_mov_b32 s0, 0x6e0000
	s_nop 0
	v_addc_co_u32_e32 v25, vcc, 0, v57, vcc
	v_add_co_u32_e32 v26, vcc, s0, v56
	s_mov_b32 s0, 0x840000
	s_nop 0
	v_addc_co_u32_e32 v27, vcc, 0, v57, vcc
	v_add_co_u32_e32 v32, vcc, s0, v56
	s_mov_b32 s0, 0x9a0000
	s_nop 0
	v_addc_co_u32_e32 v33, vcc, 0, v57, vcc
	v_add_co_u32_e32 v34, vcc, s0, v56
	s_mov_b32 s0, 0xb00000
	s_nop 0
	v_addc_co_u32_e32 v35, vcc, 0, v57, vcc
	v_add_co_u32_e32 v40, vcc, s0, v56
	s_mov_b32 s0, 0xc60000
	s_nop 0
	v_addc_co_u32_e32 v41, vcc, 0, v57, vcc
	v_add_co_u32_e32 v42, vcc, s0, v56
	s_mov_b32 s0, 0xdc0000
	s_nop 0
	v_addc_co_u32_e32 v43, vcc, 0, v57, vcc
	v_add_co_u32_e32 v48, vcc, s0, v56
	s_mov_b32 s0, 0xf20000
	s_nop 0
	v_addc_co_u32_e32 v49, vcc, 0, v57, vcc
	v_add_co_u32_e32 v50, vcc, s0, v56
	s_mov_b32 s0, 0x1080000
	s_nop 0
	v_addc_co_u32_e32 v51, vcc, 0, v57, vcc
	v_add_co_u32_e32 v58, vcc, s0, v56
	s_mov_b32 s0, 0x11e0000
	s_nop 0
	v_addc_co_u32_e32 v59, vcc, 0, v57, vcc
	v_add_co_u32_e32 v60, vcc, s0, v56
	s_mov_b32 s0, 0x1340000
	s_nop 0
	v_addc_co_u32_e32 v61, vcc, 0, v57, vcc
	v_add_co_u32_e32 v70, vcc, s0, v56
	s_mov_b32 s0, 0x14a0000
	s_nop 0
	v_addc_co_u32_e32 v71, vcc, 0, v57, vcc
	v_add_co_u32_e32 v72, vcc, s0, v56
	global_load_dwordx4 v[0:3], v[56:57], off nt
	global_load_dwordx4 v[4:7], v[8:9], off nt
	s_nop 0
	global_load_dwordx4 v[8:11], v[16:17], off nt
	global_load_dwordx4 v[12:15], v[18:19], off nt
	s_nop 0
	global_load_dwordx4 v[16:19], v[24:25], off nt
	global_load_dwordx4 v[20:23], v[26:27], off nt
	s_nop 0
	global_load_dwordx4 v[24:27], v[32:33], off nt
	global_load_dwordx4 v[28:31], v[34:35], off nt
	s_nop 0
	global_load_dwordx4 v[32:35], v[40:41], off nt
	global_load_dwordx4 v[36:39], v[42:43], off nt
	s_nop 0
	global_load_dwordx4 v[40:43], v[48:49], off nt
	global_load_dwordx4 v[44:47], v[50:51], off nt
	s_nop 0
	global_load_dwordx4 v[48:51], v[58:59], off nt
	global_load_dwordx4 v[52:55], v[60:61], off nt
	v_addc_co_u32_e32 v73, vcc, 0, v57, vcc
	global_load_dwordx4 v[56:59], v[70:71], off nt
	global_load_dwordx4 v[60:63], v[72:73], off nt
	s_waitcnt vmcnt(0)
